# layer-1 second half-FFN weights converted by the fast tile routine on the blocks idle during the RWKV recurrence
# speedup vs baseline: 1.0216x; 1.0012x over previous
; __device__ __forceinline__ void prep_weights(const Params& p, int layer, int which, float* tile, int bid, int nb) {
;     ...
;   for (int s = 0; s < 2; s++) {
;     if (!((which >> s) & 1)) continue;
;     const float* win = p.ffn_w_in + (size_t)(layer * 2 + s) * 1024 * 5632;
;     const float* wout = p.ffn_w_out + (size_t)(layer * 2 + s) * 2816 * 1024;
;     bf16_t* din = wb + (s ? W0_FIN_B : W0_FIN_A);
;     bf16_t* dout = wb + (s ? W0_FOUT_B : W0_FOUT_A);
;     wjob_run(win, din, 5632, 0, 5632, 5632, 0, 1024, 0, 1024, 1024, 1, 0, nullptr, tile, bid, nb);
;     wjob_run(wout, dout, 1024, 0, 1024, 1024, 0, 2816, 0, 2816, 2816, 0, 0, nullptr, tile, bid, nb);
; __device__ __forceinline__ void run_phase(const Params& p, int ph, char* smraw, int bid, int nb) {
;     ...
;     case 10:
;       if (nb == 512 && bid >= 256) prep_weights(p, 1, 2, smf, bid - 256, 256);
;       else { if (nb != 512) prep_weights(p, 1, 2, smf, bid, nb); rwkv_phase(p, smf, bid, nb); }
.LBB0_534:
	s_and_b64 vcc, exec, s[4:5]
	s_cbranch_vccz .LBB0_579
	v_readlane_b32 s2, v244, 27
	v_lshrrev_b32_e32 v32, 6, v2
	v_and_b32_e32 v33, 63, v2
	v_readlane_b32 s6, v247, 3
	v_readlane_b32 s7, v247, 4
	v_readfirstlane_b32 s4, v32
	s_addk_i32 s2, 0xff00
	s_lshl_b32 s2, s2, 2
	s_add_i32 s2, s2, s4
	s_movk_i32 s5, 0x400
	s_add_u32 s6, s6, 0x8200000
	s_addc_u32 s7, s7, 0
.Lwr_tile:
	s_cmp_ge_u32 s2, 0x840
	s_cbranch_scc1 .Lwr_done
	s_cmp_ge_u32 s2, 0x580
	s_cbranch_scc0 .Lwr_j0
	v_readlane_b32 s10, v246, 39
	v_readlane_b32 s11, v246, 40
	s_add_u32 s10, s10, 0x2100000
	s_addc_u32 s11, s11, 0
	s_sub_u32 s8, s2, 0x580
	s_movk_i32 s12, 0x1000
	s_mov_b32 s13, 0
	s_mov_b32 s14, 0
	s_add_u32 s16, s6, 0x1b80000
	s_addc_u32 s17, s7, 0
	s_movk_i32 s18, 0x1600
	s_movk_i32 s19, 0x0
	s_mov_b32 s20, 44
	s_branch .Lwr_go
.Lwr_j0:
	v_readlane_b32 s10, v246, 37
	v_readlane_b32 s11, v246, 38
	s_add_u32 s10, s10, 0x4200000
	s_addc_u32 s11, s11, 0
	s_mov_b32 s8, s2
	s_movk_i32 s12, 0x5800
	s_mov_b32 s13, 0
	s_mov_b32 s14, 1
	s_add_u32 s16, s6, 0x1080000
	s_addc_u32 s17, s7, 0
	s_movk_i32 s18, 0x800
	s_movk_i32 s19, 0x0
	s_mov_b32 s20, 16
	s_branch .Lwr_go

; __device__ __forceinline__ int otid() { int t = threadIdx.x; asm volatile("" : "+v"(t)); return t; }
; __device__ __forceinline__ void wjob_run(const float* jsrc, bf16_t* jdst, int jsrcld, int jsrccol0, int jncols, int jnrows, int jr0, ...
;   WJob j; j.src = jsrc; j.dst = jdst; j.mu = jmu; j.srcld = jsrcld; j.srccol0 = jsrccol0; j.ncols = jncols; j.nrows = jnrows;
;   j.r0 = jr0; j.dstld = jdstld; j.dstk0 = jdstk0; j.ksrc = jksrc; j.kjob = jkjob; j.perm = jperm; j.smode = jsmode;
;   const int tid = otid();
;   const int tn = (j.nrows + 31) >> 5, tk = j.kjob >> 5;
;   for (int t = bid; t < tn * tk; t += nb) {
;     const int n0 = (t / tk) * 32, k0 = (t % tk) * 32;
;     {
;       const int tx = tid & 31, ty = tid >> 5;
;       const int n = n0 + tx;
;       int sc = -1;
;       if (n < j.ncols) {
;         if (j.perm) { int q = n >> 5, i = n & 31; sc = (i < 16) ? (q * 16 + i) : (DFF + q * 16 + i - 16); }
;         else sc = j.srccol0 + n;
;       }
; #pragma unroll
;       for (int i = 0; i < 4; i++) {
;         const int k = k0 + ty + 8 * i;
;         float v = 0.f;
;         if (sc >= 0 && k < j.ksrc) {
;           v = j.src[(size_t)k * j.srcld + sc];
;           if (j.smode == 1) v *= j.mu[k]; else if (j.smode == 2) v *= (1.f - j.mu[k]);
;         }
;         tile[(ty + 8 * i) * 33 + tx] = v;
;       }
;     }
;     __syncthreads();
;     {
;       const int kx = tid & 31, ny = tid >> 5;
; #pragma unroll
;       for (int i = 0; i < 4; i++) {
;         const int n = n0 + ny + 8 * i;
;         if (n < j.nrows) j.dst[(size_t)(j.r0 + n) * j.dstld + j.dstk0 + k0 + kx] = f2bf(tile[kx * 33 + ny + 8 * i]);
;       }
;     }
;     __syncthreads();
;   }
; }
.Lwr_done:
	s_branch .LBB0_579
	v_readlane_b32 s0, v244, 27
	s_add_i32 s4, s0, 0xffffff00
	s_cmpk_gt_u32 s4, 0x15ff
	v_mov_b32_e32 v8, v2
	s_cbranch_scc1 .LBB0_560
	v_and_b32_e32 v16, 31, v8
	v_readlane_b32 s0, v247, 31
	s_waitcnt lgkmcnt(1)
	v_ashrrev_i32_e32 v17, 5, v8
	v_lshlrev_b32_e32 v8, 1, v16
	v_readlane_b32 s1, v247, 32
	s_waitcnt lgkmcnt(0)
	v_lshlrev_b32_e32 v12, 2, v16
	v_lshlrev_b32_e32 v13, 2, v17
	s_waitcnt vmcnt(0)
	v_lshl_add_u64 v[10:11], s[0:1], 0, v[8:9]
	s_movk_i32 s0, 0x84
	v_mul_lo_u32 v8, v17, s0
	v_readlane_b32 s0, v244, 27
	v_mul_u32_u24_e32 v14, 0x84, v16
	s_add_i32 s8, s0, 0xfffffe00
	s_lshl_b32 s0, s0, 5
	v_cmp_lt_u32_e64 s[6:7], 15, v16
	v_add_u32_e32 v18, 0xaf0, v16
	s_lshr_b32 s5, s4, 1
	s_add_i32 s9, s0, 0xffffe000
	v_add_u32_e32 v19, v12, v8
	v_add_u32_e32 v20, v13, v14
	s_branch .LBB0_538
